# adaLN modulation loop: 16 weight-row loads batched per wait instead of one HBM round trip per k; attention LDS tile write moved mid-step
# speedup vs baseline: 1.0160x; 1.0160x over previous
; #define LAS __attribute__((address_space(3)))
; __device__ __forceinline__ void attn_phase(const LArgs& a, LAS unsigned char* lds) {
;     ...
;         for (int j = 0; j < NT; ++j) {
;             const int cur = j & 1;
;             if (j + 1 < NT) ATT_LOAD(j + 1);
;             if (late && j > 0) ATT_PV(vprev, 0);
;             const LAS unsigned char* kb_ = lds + cur * KBUF;
;             f32x16 s[2];
; #pragma unroll
;             for (int kb = 0; kb < 2; ++kb) {
; #pragma unroll
;                 for (int r = 0; r < 16; ++r) s[kb][r] = 0.f;
; #pragma unroll
;                 for (int ks = 0; ks < 4; ++ks) { const bf16x8 kf = *(const LAS bf16x8*)(kb_ + (32 * kb + kappa) * KROW + mp * 128 + ks * 32 + hi * 16);
;                     s[kb] = __builtin_amdgcn_mfma_f32_32x32x16_bf16(kf, qf[ks], s[kb], 0, 0, 0); }
;             }
;             if (!late) ATT_PV_PRE(vcur);
;             float mx = s[0][0];
; #pragma unroll
;             for (int r = 1; r < 16; ++r) mx = fmaxf(mx, s[0][r]);
; #pragma unroll
;             for (int r = 0; r < 16; ++r) mx = fmaxf(mx, s[1][r]);
;             mx = fmaxf(mx, xor32_get(mx, xaddr));
;             const float mnew = fmaxf(mrun, mx);
;             if (__any(mnew > mrun)) {
;                 const float alpha = __builtin_amdgcn_exp2f(mrun - mnew); lrun *= alpha;
; #pragma unroll
;                 for (int d = 0; d < 4; ++d)
; #pragma unroll
;                     for (int r = 0; r < 16; ++r) o[d][r] *= alpha;
;                 mrun = mnew;
;             }
;             float psum = 0.f;
; #pragma unroll
;             for (int kb = 0; kb < 2; ++kb)
; #pragma unroll
;                 for (int r = 0; r < 16; ++r) { const float pv = __builtin_amdgcn_exp2f(s[kb][r] - mrun); s[kb][r] = pv; psum += pv; }
;             lrun += psum;
; #pragma unroll
;             for (int kb = 0; kb < 2; ++kb)
; #pragma unroll
;                 for (int g = 0; g < 2; ++g) {
;                     u32x4 w4; w4.x = pg8::cvt_pk_bf16(s[kb][8 * g + 0], s[kb][8 * g + 1]); w4.y = pg8::cvt_pk_bf16(s[kb][8 * g + 2], s[kb][8 * g + 3]);
;                     w4.z = pg8::cvt_pk_bf16(s[kb][8 * g + 4], s[kb][8 * g + 5]); w4.w = pg8::cvt_pk_bf16(s[kb][8 * g + 6], s[kb][8 * g + 7]);
;                     pw[2 * kb + g] = w4;
;                 }
;             if (!late) ATT_PV(vcur, 1);
;             if (j + 1 < NT) ATT_STORE(cur ^ 1, vnext);
.Lattn_noload:
	s_and_b32 s23, s21, 1
	s_mul_i32 s16, s23, 0x4400
	s_mul_i32 s24, s22, 0x4800
	v_add_u32_e32 v252, s16, v171
	v_add3_u32 v218, s24, v148, v178
	ds_read_b128 v[96:99], v252
	ds_read_b128 v[100:103], v252 offset:32
	ds_read_b128 v[104:107], v252 offset:64
	ds_read_b128 v[108:111], v252 offset:96
	ds_read_b128 v[182:185], v252 offset:8704
	ds_read_b128 v[186:189], v252 offset:8736
	ds_read_b128 v[224:227], v252 offset:8768
	ds_read_b128 v[244:247], v252 offset:8800
	s_waitcnt lgkmcnt(7)
	v_mfma_f32_32x32x16_bf16 v[228:243], v[96:99], v[112:115], v[202:217]
	s_waitcnt lgkmcnt(6)
	v_mfma_f32_32x32x16_bf16 v[228:243], v[100:103], v[116:119], v[228:243]
	s_waitcnt lgkmcnt(5)
	v_mfma_f32_32x32x16_bf16 v[228:243], v[104:107], v[120:123], v[228:243]
	s_waitcnt lgkmcnt(4)
	v_mfma_f32_32x32x16_bf16 v[228:243], v[108:111], v[124:127], v[228:243]
	ds_read_b128 v[96:99], v218 offset:34816
	ds_read_b128 v[100:103], v218 offset:39424
	ds_read_b128 v[104:107], v218 offset:44032
	ds_read_b128 v[108:111], v218 offset:48640
	s_waitcnt lgkmcnt(7)
	v_mfma_f32_32x32x16_bf16 v[64:79], v[182:185], v[112:115], v[202:217]
	s_waitcnt lgkmcnt(6)
	v_mfma_f32_32x32x16_bf16 v[64:79], v[186:189], v[116:119], v[64:79]
	s_waitcnt lgkmcnt(5)
	v_mfma_f32_32x32x16_bf16 v[64:79], v[224:227], v[120:123], v[64:79]
	s_waitcnt lgkmcnt(4)
	v_mfma_f32_32x32x16_bf16 v[64:79], v[244:247], v[124:127], v[64:79]
	ds_read_b128 v[182:185], v218 offset:34848
	ds_read_b128 v[186:189], v218 offset:39456
	ds_read_b128 v[224:227], v218 offset:44064
	ds_read_b128 v[244:247], v218 offset:48672
	s_waitcnt lgkmcnt(7)
	v_mfma_f32_32x32x16_bf16 v[48:63], v[96:99], v[92:95], v[48:63]
	v_exp_f32_e32 v228, v228
	v_exp_f32_e32 v229, v229
	v_exp_f32_e32 v230, v230
	v_exp_f32_e32 v231, v231
	s_waitcnt lgkmcnt(6)
	v_mfma_f32_32x32x16_bf16 v[32:47], v[100:103], v[92:95], v[32:47]
	v_exp_f32_e32 v232, v232
	v_exp_f32_e32 v233, v233
	v_exp_f32_e32 v234, v234
	v_exp_f32_e32 v235, v235
	s_waitcnt lgkmcnt(5)
	v_mfma_f32_32x32x16_bf16 v[16:31], v[104:107], v[92:95], v[16:31]
	v_exp_f32_e32 v236, v236
	v_exp_f32_e32 v237, v237
	v_exp_f32_e32 v238, v238
	v_exp_f32_e32 v239, v239
	s_waitcnt lgkmcnt(4)
	v_mfma_f32_32x32x16_bf16 v[0:15], v[108:111], v[92:95], v[0:15]
	v_exp_f32_e32 v240, v240
	v_exp_f32_e32 v241, v241
	v_exp_f32_e32 v242, v242
	v_exp_f32_e32 v243, v243
	ds_read_b128 v[96:99], v218 offset:34880
	ds_read_b128 v[100:103], v218 offset:39488
	ds_read_b128 v[104:107], v218 offset:44096
	ds_read_b128 v[108:111], v218 offset:48704
	s_waitcnt lgkmcnt(7)
	v_mfma_f32_32x32x16_bf16 v[48:63], v[182:185], v[88:91], v[48:63]
	v_exp_f32_e32 v64, v64
	v_exp_f32_e32 v65, v65
	v_exp_f32_e32 v66, v66
	v_exp_f32_e32 v67, v67
	s_waitcnt lgkmcnt(6)
	v_mfma_f32_32x32x16_bf16 v[32:47], v[186:189], v[88:91], v[32:47]
	v_exp_f32_e32 v68, v68
	v_exp_f32_e32 v69, v69
	v_exp_f32_e32 v70, v70
	v_exp_f32_e32 v71, v71
	s_waitcnt lgkmcnt(5)
	v_mfma_f32_32x32x16_bf16 v[16:31], v[224:227], v[88:91], v[16:31]
	v_exp_f32_e32 v72, v72
	v_exp_f32_e32 v73, v73
	v_exp_f32_e32 v74, v74
	v_exp_f32_e32 v75, v75
	s_waitcnt lgkmcnt(4)
	v_mfma_f32_32x32x16_bf16 v[0:15], v[244:247], v[88:91], v[0:15]
	v_exp_f32_e32 v76, v76
	v_exp_f32_e32 v77, v77
	v_exp_f32_e32 v78, v78
	v_exp_f32_e32 v79, v79
	s_andn2_b64 vcc, exec, s[0:1]
	s_cbranch_vccnz .Lattn_nowrite
	s_xor_b32 s0, s23, 1
	s_mulk_i32 s0, 0x4400
	s_mul_i32 s1, s20, 0x4800
	v_add_u32_e32 v219, s0, v168
	s_waitcnt vmcnt(3)
	ds_write_b128 v219, v[128:131]
	s_waitcnt vmcnt(2)
	ds_write_b128 v219, v[132:135] offset:8704
	v_add_u32_e32 v219, s1, v169
	s_waitcnt vmcnt(1)
	ds_write_b128 v219, v[136:139] offset:34816
	s_waitcnt vmcnt(0)
	ds_write_b128 v219, v[140:143] offset:44032
.Lattn_nowrite:
	ds_read_b128 v[182:185], v218 offset:34912
	ds_read_b128 v[186:189], v218 offset:39520
	ds_read_b128 v[224:227], v218 offset:44128
	ds_read_b128 v[244:247], v218 offset:48736
	s_waitcnt lgkmcnt(7)
	v_mfma_f32_32x32x16_bf16 v[48:63], v[96:99], v[84:87], v[48:63]
	v_add_f32_e32 v190, v228, v229
	v_add_f32_e32 v191, v64, v65
	v_add_f32_e32 v190, v190, v230
	v_add_f32_e32 v191, v191, v66
	v_add_f32_e32 v190, v190, v231
	v_add_f32_e32 v191, v191, v67
	s_waitcnt lgkmcnt(6)
	v_mfma_f32_32x32x16_bf16 v[32:47], v[100:103], v[84:87], v[32:47]
	v_add_f32_e32 v190, v190, v232
	v_add_f32_e32 v191, v191, v68
	v_add_f32_e32 v190, v190, v233
	v_add_f32_e32 v191, v191, v69
	v_add_f32_e32 v190, v190, v234
	v_add_f32_e32 v191, v191, v70
	s_waitcnt lgkmcnt(5)
	v_mfma_f32_32x32x16_bf16 v[16:31], v[104:107], v[84:87], v[16:31]
	v_add_f32_e32 v190, v190, v235
	v_add_f32_e32 v191, v191, v71
	v_add_f32_e32 v190, v190, v236
	v_add_f32_e32 v191, v191, v72
	v_add_f32_e32 v190, v190, v237
	v_add_f32_e32 v191, v191, v73
	s_waitcnt lgkmcnt(4)
	v_mfma_f32_32x32x16_bf16 v[0:15], v[108:111], v[84:87], v[0:15]
	v_add_f32_e32 v190, v190, v238
	v_add_f32_e32 v191, v191, v74
	v_add_f32_e32 v190, v190, v239
	v_add_f32_e32 v191, v191, v75
	v_add_f32_e32 v190, v190, v240
	v_add_f32_e32 v191, v191, v76
	s_waitcnt lgkmcnt(3)
	v_mfma_f32_32x32x16_bf16 v[48:63], v[182:185], v[80:83], v[48:63]
	v_add_f32_e32 v190, v190, v241
	v_add_f32_e32 v191, v191, v77
	v_add_f32_e32 v190, v190, v242
	v_add_f32_e32 v191, v191, v78
	s_waitcnt lgkmcnt(2)
	v_mfma_f32_32x32x16_bf16 v[32:47], v[186:189], v[80:83], v[32:47]
	v_add_f32_e32 v190, v190, v243
	v_add_f32_e32 v191, v191, v79
	v_add_f32_e32 v190, v190, v191
	s_waitcnt lgkmcnt(1)
	v_mfma_f32_32x32x16_bf16 v[16:31], v[224:227], v[80:83], v[16:31]
	v_cvt_pk_bf16_f32 v92, v228, v229
	v_cvt_pk_bf16_f32 v93, v230, v231
	v_cvt_pk_bf16_f32 v94, v232, v233
	v_cvt_pk_bf16_f32 v95, v234, v235
	s_waitcnt lgkmcnt(0)
	v_mfma_f32_32x32x16_bf16 v[0:15], v[244:247], v[80:83], v[0:15]
	v_cvt_pk_bf16_f32 v88, v236, v237
	v_cvt_pk_bf16_f32 v89, v238, v239
	v_cvt_pk_bf16_f32 v90, v240, v241
	v_cvt_pk_bf16_f32 v91, v242, v243
	v_cmp_lt_f32_e32 vcc, 0x43800000, v190
	s_cbranch_vccnz .Lattn_rare
	v_add_f32_e32 v149, v149, v190
	v_cvt_pk_bf16_f32 v84, v64, v65
	v_cvt_pk_bf16_f32 v85, v66, v67
	v_cvt_pk_bf16_f32 v86, v68, v69
	v_cvt_pk_bf16_f32 v87, v70, v71
	v_cvt_pk_bf16_f32 v80, v72, v73
	v_cvt_pk_bf16_f32 v81, v74, v75
	v_cvt_pk_bf16_f32 v82, v76, v77
	v_cvt_pk_bf16_f32 v83, v78, v79

; __device__ __forceinline__ float silu_f(float x) { return x * __builtin_amdgcn_rcpf(1.f + __builtin_amdgcn_exp2f(-x * 1.4426950408889634f)); }
; __device__ __forceinline__ void p0_prologue(const LArgs& a, LAS unsigned char* lds) {
;     ...
;         for (int it = gw; it < 3072; it += NGW) {
;             const int layer = it / 1536, r = it % 1536, cc = r >> 3, kc = r & 7, col = cc * 64 + lane;
;             const float* w = a.in(I_ADAW) + (size_t)layer * 2048 * 12288 + (size_t)(kc * 256) * 12288 + col;
;             const float* c0 = a.in(I_C) + kc * 256; const float* c1 = c0 + 2048; const float* c2 = a.in(I_CCTX) + kc * 256;
;             float a0 = 0.f, a1 = 0.f, a2 = 0.f;
; #pragma unroll 8
;             for (int k = 0; k < 256; ++k) { const float wv = w[(size_t)k * 12288]; a0 += pg8::silu_f(c0[k]) * wv; a1 += pg8::silu_f(c1[k]) * wv; a2 += pg8::silu_f(c2[k]) * wv; }
.LBB0_473:
	v_lshl_add_u64 v[8:9], v[30:31], 0, s[6:7]
	v_lshl_add_u64 v[44:45], v[32:33], 0, s[6:7]
	v_lshl_add_u64 v[10:11], v[8:9], 0, s[92:93]
	s_mov_b32 s2, 0xfffac000
	s_mov_b32 s3, -1
	v_lshl_add_u64 v[54:55], v[34:35], 0, s[2:3]
	global_load_dword v100, v[54:55], off
	s_mov_b64 s[2:3], 0xc000
	v_lshl_add_u64 v[56:57], v[54:55], 0, s[2:3]
	global_load_dword v101, v[56:57], off
	s_mov_b64 s[2:3], 0x18000
	v_lshl_add_u64 v[56:57], v[54:55], 0, s[2:3]
	global_load_dword v102, v[56:57], off
	s_mov_b64 s[2:3], 0x24000
	v_lshl_add_u64 v[56:57], v[54:55], 0, s[2:3]
	global_load_dword v103, v[56:57], off
	s_mov_b64 s[2:3], 0x30000
	v_lshl_add_u64 v[56:57], v[54:55], 0, s[2:3]
	global_load_dword v104, v[56:57], off
	s_mov_b64 s[2:3], 0x3c000
	v_lshl_add_u64 v[56:57], v[54:55], 0, s[2:3]
	global_load_dword v105, v[56:57], off
	s_mov_b64 s[2:3], 0x48000
	v_lshl_add_u64 v[56:57], v[54:55], 0, s[2:3]
	global_load_dword v106, v[56:57], off
	s_mov_b64 s[2:3], 0x54000
	v_lshl_add_u64 v[56:57], v[54:55], 0, s[2:3]
	global_load_dword v107, v[56:57], off
	s_mov_b64 s[2:3], 0x60000
	v_lshl_add_u64 v[56:57], v[54:55], 0, s[2:3]
	global_load_dword v108, v[56:57], off
	s_mov_b64 s[2:3], 0x6c000
	v_lshl_add_u64 v[56:57], v[54:55], 0, s[2:3]
	global_load_dword v109, v[56:57], off
	s_mov_b64 s[2:3], 0x78000
	v_lshl_add_u64 v[56:57], v[54:55], 0, s[2:3]
	global_load_dword v110, v[56:57], off
	s_mov_b64 s[2:3], 0x84000
	v_lshl_add_u64 v[56:57], v[54:55], 0, s[2:3]
	global_load_dword v111, v[56:57], off
	s_mov_b64 s[2:3], 0x90000
	v_lshl_add_u64 v[56:57], v[54:55], 0, s[2:3]
	global_load_dword v112, v[56:57], off
	s_mov_b64 s[2:3], 0x9c000
	v_lshl_add_u64 v[56:57], v[54:55], 0, s[2:3]
	global_load_dword v113, v[56:57], off
	s_mov_b64 s[2:3], 0xa8000
	v_lshl_add_u64 v[56:57], v[54:55], 0, s[2:3]
	global_load_dword v114, v[56:57], off
	s_mov_b64 s[2:3], 0xb4000
	v_lshl_add_u64 v[56:57], v[54:55], 0, s[2:3]
	global_load_dword v115, v[56:57], off
	global_load_dwordx4 v[60:63], v[8:9], off
	global_load_dwordx4 v[76:79], v[10:11], off
	global_load_dwordx4 v[120:123], v[44:45], off
	global_load_dwordx4 v[64:67], v[8:9], off offset:16
	global_load_dwordx4 v[80:83], v[10:11], off offset:16
	global_load_dwordx4 v[124:127], v[44:45], off offset:16
	global_load_dwordx4 v[68:71], v[8:9], off offset:32
	global_load_dwordx4 v[84:87], v[10:11], off offset:32
	global_load_dwordx4 v[128:131], v[44:45], off offset:32
	global_load_dwordx4 v[72:75], v[8:9], off offset:48
	global_load_dwordx4 v[88:91], v[10:11], off offset:48
	global_load_dwordx4 v[132:135], v[44:45], off offset:48
	s_mov_b64 s[2:3], 0xc0000
	v_lshl_add_u64 v[34:35], v[34:35], 0, s[2:3]
	s_add_u32 s6, s6, 64
	s_addc_u32 s7, s7, 0
	s_waitcnt vmcnt(0)
	v_mul_f32_e32 v4, 0xbfb8aa3b, v60
	v_mul_f32_e32 v5, 0xbfb8aa3b, v76
	v_mul_f32_e32 v6, 0xbfb8aa3b, v120
	v_exp_f32_e32 v4, v4
	v_exp_f32_e32 v5, v5
	v_exp_f32_e32 v6, v6
	v_add_f32_e32 v4, 1.0, v4
	v_add_f32_e32 v5, 1.0, v5
	v_add_f32_e32 v6, 1.0, v6
	v_rcp_f32_e32 v4, v4
	v_rcp_f32_e32 v5, v5
	v_rcp_f32_e32 v6, v6
	v_mul_f32_e32 v4, v60, v4
	v_mul_f32_e32 v5, v76, v5
	v_mul_f32_e32 v6, v120, v6
	v_fmac_f32_e32 v42, v100, v4
	v_fmac_f32_e32 v37, v100, v5
	v_fmac_f32_e32 v36, v100, v6
	v_mul_f32_e32 v4, 0xbfb8aa3b, v61
	v_mul_f32_e32 v5, 0xbfb8aa3b, v77
	v_mul_f32_e32 v6, 0xbfb8aa3b, v121
	v_exp_f32_e32 v4, v4
	v_exp_f32_e32 v5, v5
	v_exp_f32_e32 v6, v6
	v_add_f32_e32 v4, 1.0, v4
	v_add_f32_e32 v5, 1.0, v5
	v_add_f32_e32 v6, 1.0, v6
	v_rcp_f32_e32 v4, v4
	v_rcp_f32_e32 v5, v5
	v_rcp_f32_e32 v6, v6
	v_mul_f32_e32 v4, v61, v4
	v_mul_f32_e32 v5, v77, v5
	v_mul_f32_e32 v6, v121, v6
	v_fmac_f32_e32 v42, v101, v4
	v_fmac_f32_e32 v37, v101, v5
	v_fmac_f32_e32 v36, v101, v6
	v_mul_f32_e32 v4, 0xbfb8aa3b, v62
	v_mul_f32_e32 v5, 0xbfb8aa3b, v78
	v_mul_f32_e32 v6, 0xbfb8aa3b, v122
	v_exp_f32_e32 v4, v4
	v_exp_f32_e32 v5, v5
	v_exp_f32_e32 v6, v6
	v_add_f32_e32 v4, 1.0, v4
	v_add_f32_e32 v5, 1.0, v5
	v_add_f32_e32 v6, 1.0, v6
	v_rcp_f32_e32 v4, v4
	v_rcp_f32_e32 v5, v5
	v_rcp_f32_e32 v6, v6
	v_mul_f32_e32 v4, v62, v4
	v_mul_f32_e32 v5, v78, v5
	v_mul_f32_e32 v6, v122, v6
	v_fmac_f32_e32 v42, v102, v4
	v_fmac_f32_e32 v37, v102, v5
	v_fmac_f32_e32 v36, v102, v6
	v_mul_f32_e32 v4, 0xbfb8aa3b, v63
	v_mul_f32_e32 v5, 0xbfb8aa3b, v79
	v_mul_f32_e32 v6, 0xbfb8aa3b, v123
	v_exp_f32_e32 v4, v4
	v_exp_f32_e32 v5, v5
	v_exp_f32_e32 v6, v6
	v_add_f32_e32 v4, 1.0, v4
	v_add_f32_e32 v5, 1.0, v5
	v_add_f32_e32 v6, 1.0, v6
	v_rcp_f32_e32 v4, v4
	v_rcp_f32_e32 v5, v5
	v_rcp_f32_e32 v6, v6
	v_mul_f32_e32 v4, v63, v4
	v_mul_f32_e32 v5, v79, v5
	v_mul_f32_e32 v6, v123, v6
	v_fmac_f32_e32 v42, v103, v4
	v_fmac_f32_e32 v37, v103, v5
	v_fmac_f32_e32 v36, v103, v6
	v_mul_f32_e32 v4, 0xbfb8aa3b, v64
	v_mul_f32_e32 v5, 0xbfb8aa3b, v80
	v_mul_f32_e32 v6, 0xbfb8aa3b, v124
	v_exp_f32_e32 v4, v4
	v_exp_f32_e32 v5, v5
	v_exp_f32_e32 v6, v6
	v_add_f32_e32 v4, 1.0, v4
	v_add_f32_e32 v5, 1.0, v5
	v_add_f32_e32 v6, 1.0, v6
	v_rcp_f32_e32 v4, v4
	v_rcp_f32_e32 v5, v5
	v_rcp_f32_e32 v6, v6
	v_mul_f32_e32 v4, v64, v4
	v_mul_f32_e32 v5, v80, v5
	v_mul_f32_e32 v6, v124, v6
	v_fmac_f32_e32 v42, v104, v4
	v_fmac_f32_e32 v37, v104, v5
	v_fmac_f32_e32 v36, v104, v6
	v_mul_f32_e32 v4, 0xbfb8aa3b, v65
	v_mul_f32_e32 v5, 0xbfb8aa3b, v81
	v_mul_f32_e32 v6, 0xbfb8aa3b, v125
	v_exp_f32_e32 v4, v4
	v_exp_f32_e32 v5, v5
	v_exp_f32_e32 v6, v6
	v_add_f32_e32 v4, 1.0, v4
	v_add_f32_e32 v5, 1.0, v5
	v_add_f32_e32 v6, 1.0, v6
	v_rcp_f32_e32 v4, v4
	v_rcp_f32_e32 v5, v5
	v_rcp_f32_e32 v6, v6
	v_mul_f32_e32 v4, v65, v4
	v_mul_f32_e32 v5, v81, v5
	v_mul_f32_e32 v6, v125, v6
; __device__ __forceinline__ float silu_f(float x) { return x * __builtin_amdgcn_rcpf(1.f + __builtin_amdgcn_exp2f(-x * 1.4426950408889634f)); }
; __device__ __forceinline__ void p0_prologue(const LArgs& a, LAS unsigned char* lds) {
;     ...
;             for (int k = 0; k < 256; ++k) { const float wv = w[(size_t)k * 12288]; a0 += pg8::silu_f(c0[k]) * wv; a1 += pg8::silu_f(c1[k]) * wv; a2 += pg8::silu_f(c2[k]) * wv; }
;             if (kc == 0) { const float bb = a.in(I_ADAB)[layer * 12288 + col]; a0 += bb; a1 += bb; a2 += bb; }
;             float* m = mods + (size_t)layer * 3 * 12288 + col;
;             atomicAdd(m, a0); atomicAdd(m + 12288, a1); atomicAdd(m + 2 * 12288, a2);
	v_fmac_f32_e32 v42, v105, v4
	v_fmac_f32_e32 v37, v105, v5
	v_fmac_f32_e32 v36, v105, v6
	v_mul_f32_e32 v4, 0xbfb8aa3b, v66
	v_mul_f32_e32 v5, 0xbfb8aa3b, v82
	v_mul_f32_e32 v6, 0xbfb8aa3b, v126
	v_exp_f32_e32 v4, v4
	v_exp_f32_e32 v5, v5
	v_exp_f32_e32 v6, v6
	v_add_f32_e32 v4, 1.0, v4
	v_add_f32_e32 v5, 1.0, v5
	v_add_f32_e32 v6, 1.0, v6
	v_rcp_f32_e32 v4, v4
	v_rcp_f32_e32 v5, v5
	v_rcp_f32_e32 v6, v6
	v_mul_f32_e32 v4, v66, v4
	v_mul_f32_e32 v5, v82, v5
	v_mul_f32_e32 v6, v126, v6
	v_fmac_f32_e32 v42, v106, v4
	v_fmac_f32_e32 v37, v106, v5
	v_fmac_f32_e32 v36, v106, v6
	v_mul_f32_e32 v4, 0xbfb8aa3b, v67
	v_mul_f32_e32 v5, 0xbfb8aa3b, v83
	v_mul_f32_e32 v6, 0xbfb8aa3b, v127
	v_exp_f32_e32 v4, v4
	v_exp_f32_e32 v5, v5
	v_exp_f32_e32 v6, v6
	v_add_f32_e32 v4, 1.0, v4
	v_add_f32_e32 v5, 1.0, v5
	v_add_f32_e32 v6, 1.0, v6
	v_rcp_f32_e32 v4, v4
	v_rcp_f32_e32 v5, v5
	v_rcp_f32_e32 v6, v6
	v_mul_f32_e32 v4, v67, v4
	v_mul_f32_e32 v5, v83, v5
	v_mul_f32_e32 v6, v127, v6
	v_fmac_f32_e32 v42, v107, v4
	v_fmac_f32_e32 v37, v107, v5
	v_fmac_f32_e32 v36, v107, v6
	v_mul_f32_e32 v4, 0xbfb8aa3b, v68
	v_mul_f32_e32 v5, 0xbfb8aa3b, v84
	v_mul_f32_e32 v6, 0xbfb8aa3b, v128
	v_exp_f32_e32 v4, v4
	v_exp_f32_e32 v5, v5
	v_exp_f32_e32 v6, v6
	v_add_f32_e32 v4, 1.0, v4
	v_add_f32_e32 v5, 1.0, v5
	v_add_f32_e32 v6, 1.0, v6
	v_rcp_f32_e32 v4, v4
	v_rcp_f32_e32 v5, v5
	v_rcp_f32_e32 v6, v6
	v_mul_f32_e32 v4, v68, v4
	v_mul_f32_e32 v5, v84, v5
	v_mul_f32_e32 v6, v128, v6
	v_fmac_f32_e32 v42, v108, v4
	v_fmac_f32_e32 v37, v108, v5
	v_fmac_f32_e32 v36, v108, v6
	v_mul_f32_e32 v4, 0xbfb8aa3b, v69
	v_mul_f32_e32 v5, 0xbfb8aa3b, v85
	v_mul_f32_e32 v6, 0xbfb8aa3b, v129
	v_exp_f32_e32 v4, v4
	v_exp_f32_e32 v5, v5
	v_exp_f32_e32 v6, v6
	v_add_f32_e32 v4, 1.0, v4
	v_add_f32_e32 v5, 1.0, v5
	v_add_f32_e32 v6, 1.0, v6
	v_rcp_f32_e32 v4, v4
	v_rcp_f32_e32 v5, v5
	v_rcp_f32_e32 v6, v6
	v_mul_f32_e32 v4, v69, v4
	v_mul_f32_e32 v5, v85, v5
	v_mul_f32_e32 v6, v129, v6
	v_fmac_f32_e32 v42, v109, v4
	v_fmac_f32_e32 v37, v109, v5
	v_fmac_f32_e32 v36, v109, v6
	v_mul_f32_e32 v4, 0xbfb8aa3b, v70
	v_mul_f32_e32 v5, 0xbfb8aa3b, v86
	v_mul_f32_e32 v6, 0xbfb8aa3b, v130
	v_exp_f32_e32 v4, v4
	v_exp_f32_e32 v5, v5
	v_exp_f32_e32 v6, v6
	v_add_f32_e32 v4, 1.0, v4
	v_add_f32_e32 v5, 1.0, v5
	v_add_f32_e32 v6, 1.0, v6
	v_rcp_f32_e32 v4, v4
	v_rcp_f32_e32 v5, v5
	v_rcp_f32_e32 v6, v6
	v_mul_f32_e32 v4, v70, v4
	v_mul_f32_e32 v5, v86, v5
	v_mul_f32_e32 v6, v130, v6
	v_fmac_f32_e32 v42, v110, v4
	v_fmac_f32_e32 v37, v110, v5
	v_fmac_f32_e32 v36, v110, v6
	v_mul_f32_e32 v4, 0xbfb8aa3b, v71
	v_mul_f32_e32 v5, 0xbfb8aa3b, v87
	v_mul_f32_e32 v6, 0xbfb8aa3b, v131
	v_exp_f32_e32 v4, v4
	v_exp_f32_e32 v5, v5
	v_exp_f32_e32 v6, v6
	v_add_f32_e32 v4, 1.0, v4
	v_add_f32_e32 v5, 1.0, v5
	v_add_f32_e32 v6, 1.0, v6
	v_rcp_f32_e32 v4, v4
	v_rcp_f32_e32 v5, v5
	v_rcp_f32_e32 v6, v6
	v_mul_f32_e32 v4, v71, v4
	v_mul_f32_e32 v5, v87, v5
	v_mul_f32_e32 v6, v131, v6
	v_fmac_f32_e32 v42, v111, v4
	v_fmac_f32_e32 v37, v111, v5
	v_fmac_f32_e32 v36, v111, v6
	v_mul_f32_e32 v4, 0xbfb8aa3b, v72
	v_mul_f32_e32 v5, 0xbfb8aa3b, v88
	v_mul_f32_e32 v6, 0xbfb8aa3b, v132
	v_exp_f32_e32 v4, v4
	v_exp_f32_e32 v5, v5
	v_exp_f32_e32 v6, v6
	v_add_f32_e32 v4, 1.0, v4
	v_add_f32_e32 v5, 1.0, v5
	v_add_f32_e32 v6, 1.0, v6
	v_rcp_f32_e32 v4, v4
	v_rcp_f32_e32 v5, v5
	v_rcp_f32_e32 v6, v6
	v_mul_f32_e32 v4, v72, v4
	v_mul_f32_e32 v5, v88, v5
	v_mul_f32_e32 v6, v132, v6
	v_fmac_f32_e32 v42, v112, v4
	v_fmac_f32_e32 v37, v112, v5
	v_fmac_f32_e32 v36, v112, v6
	v_mul_f32_e32 v4, 0xbfb8aa3b, v73
	v_mul_f32_e32 v5, 0xbfb8aa3b, v89
	v_mul_f32_e32 v6, 0xbfb8aa3b, v133
	v_exp_f32_e32 v4, v4
	v_exp_f32_e32 v5, v5
	v_exp_f32_e32 v6, v6
	v_add_f32_e32 v4, 1.0, v4
	v_add_f32_e32 v5, 1.0, v5
	v_add_f32_e32 v6, 1.0, v6
	v_rcp_f32_e32 v4, v4
	v_rcp_f32_e32 v5, v5
	v_rcp_f32_e32 v6, v6
	v_mul_f32_e32 v4, v73, v4
	v_mul_f32_e32 v5, v89, v5
	v_mul_f32_e32 v6, v133, v6
	v_fmac_f32_e32 v42, v113, v4
	v_fmac_f32_e32 v37, v113, v5
	v_fmac_f32_e32 v36, v113, v6
	v_mul_f32_e32 v4, 0xbfb8aa3b, v74
	v_mul_f32_e32 v5, 0xbfb8aa3b, v90
	v_mul_f32_e32 v6, 0xbfb8aa3b, v134
	v_exp_f32_e32 v4, v4
	v_exp_f32_e32 v5, v5
	v_exp_f32_e32 v6, v6
	v_add_f32_e32 v4, 1.0, v4
	v_add_f32_e32 v5, 1.0, v5
	v_add_f32_e32 v6, 1.0, v6
	v_rcp_f32_e32 v4, v4
	v_rcp_f32_e32 v5, v5
	v_rcp_f32_e32 v6, v6
	v_mul_f32_e32 v4, v74, v4
	v_mul_f32_e32 v5, v90, v5
	v_mul_f32_e32 v6, v134, v6
	v_fmac_f32_e32 v42, v114, v4
	v_fmac_f32_e32 v37, v114, v5
	v_fmac_f32_e32 v36, v114, v6
	v_mul_f32_e32 v4, 0xbfb8aa3b, v75
	v_mul_f32_e32 v5, 0xbfb8aa3b, v91
	v_mul_f32_e32 v6, 0xbfb8aa3b, v135
	v_exp_f32_e32 v4, v4
	v_exp_f32_e32 v5, v5
	v_exp_f32_e32 v6, v6
	v_add_f32_e32 v4, 1.0, v4
	v_add_f32_e32 v5, 1.0, v5
	v_add_f32_e32 v6, 1.0, v6
	v_rcp_f32_e32 v4, v4
	v_rcp_f32_e32 v5, v5
	v_rcp_f32_e32 v6, v6
	v_mul_f32_e32 v4, v75, v4
	v_mul_f32_e32 v5, v91, v5
	v_mul_f32_e32 v6, v135, v6
	v_fmac_f32_e32 v42, v115, v4
	v_fmac_f32_e32 v37, v115, v5
	v_fmac_f32_e32 v36, v115, v6
	s_cmpk_eq_i32 s6, 0x400
	s_cbranch_scc0 .LBB0_473
	v_cmp_eq_u32_e32 vcc, 0, v43
	s_and_saveexec_b64 s[6:7], vcc
	s_cbranch_execz .LBB0_471
	v_mov_b32_e32 v4, s65
	ds_read_b64 v[4:5], v4 offset:40
	v_mad_i32_i24 v6, v41, s10, v28
	v_ashrrev_i32_e32 v7, 31, v6
	s_waitcnt lgkmcnt(0)
	v_readfirstlane_b32 s2, v5
	v_readfirstlane_b32 s3, v4
	s_nop 0
	v_mov_b32_e32 v5, s2
	v_mov_b32_e32 v4, s3
	v_lshl_add_u64 v[4:5], v[6:7], 2, v[4:5]
	global_load_dword v4, v[4:5], off
	s_waitcnt vmcnt(0)
	v_add_f32_e32 v42, v42, v4
	v_pk_add_f32 v[36:37], v[36:37], v[4:5] op_sel_hi:[1,0]
	s_branch .LBB0_471
